# phase 3 context-token prep pass moved from workgroups 0-31 (four GEMM tiles) to workgroups 128-159 (three GEMM tiles)
# baseline (speedup 1.0000x reference)
; __device__ __forceinline__ void prep_tokens(const bf16* Y, bf16* MIX, const float* scw, int tb, int te, int wi, int ws_, int lane) {
;     int inp_ = INP; asm volatile("" : "+s"(inp_));
;     const int ch = 4 * lane, grp = lane >> 4, hw = 1 << grp;
;     const f32x4 cw0 = *(const f32x4*)(scw + ch), cw1 = *(const f32x4*)(scw + 256 + ch), cw2 = *(const f32x4*)(scw + 512 + ch);
;     for (int t0 = tb + wi * 4; t0 < te; t0 += ws_ * 4)
;     for (int ti = 0; ti < 4; ++ti) { const int t = t0 + ti;
;         const bf16* y = Y + (size_t)t * INP; const bool lat = t < TLAT; const int n = lat ? (t & (SEQ - 1)) : ((t - TLAT) & (CTXL - 1)); const int len = lat ? SEQ : CTXL;
;         const bool hp = n > 0, hn = n < len - 1; const long op = hp ? -(long)inp_ : 0, on = hn ? (long)inp_ : 0; const float fp = hp ? 1.f : 0.f, fn = hn ? 1.f : 0.f;
; __global__ void __launch_bounds__(512) mega(Params p) {
;     ...
;                 if (k == 3) { DEF_TID prep_tokens(Y, MIX, p.in[19] + L * 3 * 256, TLAT, TT, gw, NGW, lane); }
.LBB0_558:
	v_readlane_b32 s52, v253, 47
	s_nop 3
	s_and_b32 s0, s52, 7
	s_lshr_b32 s1, s52, 3
	v_writelane_b32 v253, s0, 8
	v_writelane_b32 v253, s1, 9
	s_nop 0
	v_readlane_b32 s0, v254, 40
	v_readlane_b32 s1, v254, 41
	s_and_b64 vcc, exec, s[0:1]
	s_cbranch_vccz .LBB0_579
	v_mov_b32_e32 v0, v242
	v_readlane_b32 s1, v253, 24
	v_readfirstlane_b32 s0, v0
	s_ashr_i32 s0, s0, 4
	s_and_b32 s0, s0, -4
	s_add_i32 s0, s0, s1
	s_sub_i32 s0, s0, 0x1000
	s_and_b32 s0, s0, 0x1fff
	s_movk_i32 s26, 0x600
	s_cmpk_gt_i32 s0, 0x3ff
	s_cbranch_scc1 .LBB0_579
	v_writelane_b32 v254, s88, 11
	s_load_dwordx2 s[2:3], s[90:91], 0x98
	v_and_b32_e32 v12, 63, v0
	v_writelane_b32 v254, s89, 12
	v_lshlrev_b32_e32 v8, 4, v12
	v_readlane_b32 s1, v254, 5
	s_mul_i32 s4, s1, 0x300
	s_ashr_i32 s5, s4, 31
	s_lshl_b64 s[4:5], s[4:5], 2
	s_waitcnt lgkmcnt(0)
	s_add_u32 s2, s2, s4
	s_addc_u32 s3, s3, s5
	v_bfe_u32 v13, v0, 4, 2
	global_load_dwordx4 v[0:3], v8, s[2:3]
	global_load_dwordx4 v[4:7], v8, s[2:3] offset:2048
	s_add_i32 s28, s0, 0x8000
	global_load_dwordx4 v[8:11], v8, s[2:3] offset:1024
	s_ashr_i32 s27, s26, 31
	s_sub_u32 s2, 0, s26
	s_subb_u32 s3, 0, s27
	s_lshl_b64 s[10:11], s[26:27], 3
	s_sub_u32 s52, 0, s10
	s_subb_u32 s68, 0, s11
	s_lshl_b64 s[12:13], s[26:27], 2
	s_sub_u32 s33, 0, s12
	s_subb_u32 s40, 0, s13
	s_lshl_b64 s[14:15], s[26:27], 1
	s_sub_u32 s1, 0, s14
	s_subb_u32 s69, 0, s15
	s_ashr_i32 s29, s28, 31
	s_mov_b64 s[38:39], s[30:31]
	s_lshl_b64 s[16:17], s[28:29], 11
	s_add_u32 s30, s38, s16
	s_addc_u32 s31, s39, s17
	s_add_u32 s16, s38, 0xa200380
	s_mul_i32 s24, s26, 14
	s_addc_u32 s17, s39, 0
	s_mul_i32 s29, s28, 0xc00
	s_mul_hi_i32 s23, s26, 14
	s_mul_hi_i32 s25, s28, 0xc00
	s_add_u32 s24, s29, s24
	s_addc_u32 s23, s25, s23
	s_add_u32 s34, s16, s24
	s_mul_i32 s22, s26, 12
	s_addc_u32 s35, s17, s23
	s_mul_hi_i32 s21, s26, 12
	s_add_u32 s22, s29, s22
	s_addc_u32 s21, s25, s21
	s_add_u32 s36, s16, s22
	s_addc_u32 s37, s17, s21
	s_add_u32 s46, s38, s29
	s_mul_i32 s20, s26, 10
	s_addc_u32 s47, s39, s25
	s_mul_hi_i32 s19, s26, 10
	s_add_u32 s20, s29, s20
	s_addc_u32 s19, s25, s19
	s_add_u32 s48, s16, s20
	s_addc_u32 s49, s17, s19
	s_add_u32 s10, s29, s10
	s_addc_u32 s11, s25, s11
	s_add_u32 s50, s16, s10
	s_mul_i32 s18, s26, 6
	s_addc_u32 s51, s17, s11
	s_mul_hi_i32 s0, s26, 6
	s_add_u32 s10, s29, s18
	s_addc_u32 s0, s25, s0
	s_add_u32 s54, s16, s10
	s_addc_u32 s55, s17, s0
	s_add_u32 s0, s29, s14
	s_addc_u32 s10, s25, s15
	s_add_u32 s56, s16, s0
	s_addc_u32 s57, s17, s10
	s_add_u32 s0, s29, s12
	s_addc_u32 s10, s25, s13
	s_add_u32 s58, s16, s0
	v_lshlrev_b32_e64 v45, v13, 1
	v_cmp_eq_u32_e64 s[4:5], 3, v13
	v_cmp_lt_u32_e64 s[6:7], 31, v12
	v_cmp_lt_u32_e64 s[8:9], 15, v12
	v_lshlrev_b32_e32 v208, 3, v12
	s_addc_u32 s59, s17, s10
	s_branch .LBB0_562
